# P11 attention weights: xor-32 cross-half shuffles via two v_permlane32_swap instead of ds_bpermute LDS round trips (v59 + attnshfl)
# baseline (speedup 1.0000x reference)
.LBB0_1340:
	v_cmp_eq_f32_e32 vcc, 0, v171
	s_nop 1
	s_cmp_eq_u64 vcc, exec
	s_cbranch_scc1 .LBB0_1346
	s_cmp_ge_i32 s12, s40
	s_cbranch_scc1 .LBB0_1346
	ds_read_b128 v[2:5], v204 offset:16384
	ds_read_b128 v[6:9], v204 offset:24576
	ds_read_b128 v[10:13], v205 offset:16384
	ds_read_b128 v[250:253], v205 offset:24576
	s_or_b32 s13, s12, 63
	s_mov_b64 s[10:11], -1
	s_cmp_lt_i32 s13, s39
	s_waitcnt lgkmcnt(3)
	v_mfma_f32_32x32x16_bf16 v[80:95], v[2:5], v[112:115], 0
	v_mbcnt_hi_u32_b32 v173, -1, v214
	ds_read_b128 v[2:5], v206 offset:16384
	s_waitcnt lgkmcnt(3)
	v_mfma_f32_32x32x16_bf16 v[96:111], v[6:9], v[112:115], 0
	ds_read_b128 v[6:9], v206 offset:24576
	s_waitcnt lgkmcnt(3)
	v_mfma_f32_32x32x16_bf16 v[80:95], v[10:13], v[116:119], v[80:95]
	ds_read_b128 v[10:13], v207 offset:16384
	s_waitcnt lgkmcnt(3)
	v_mfma_f32_32x32x16_bf16 v[96:111], v[250:253], v[116:119], v[96:111]
	ds_read_b128 v[250:253], v207 offset:24576
	s_waitcnt lgkmcnt(3)
	v_mfma_f32_32x32x16_bf16 v[80:95], v[2:5], v[120:123], v[80:95]
	ds_read_b128 v[2:5], v208 offset:16384
	s_waitcnt lgkmcnt(3)
	v_mfma_f32_32x32x16_bf16 v[96:111], v[6:9], v[120:123], v[96:111]
	ds_read_b128 v[6:9], v208 offset:24576
	s_waitcnt lgkmcnt(3)
	v_mfma_f32_32x32x16_bf16 v[80:95], v[10:13], v[124:127], v[80:95]
	ds_read_b128 v[10:13], v209 offset:24576
	s_waitcnt lgkmcnt(3)
	v_mfma_f32_32x32x16_bf16 v[96:111], v[250:253], v[124:127], v[96:111]
	ds_read_b128 v[250:253], v210 offset:24576
	s_waitcnt lgkmcnt(3)
	v_mfma_f32_32x32x16_bf16 v[80:95], v[2:5], v[128:131], v[80:95]
	ds_read_b128 v[2:5], v209 offset:16384
	s_waitcnt lgkmcnt(3)
	v_mfma_f32_32x32x16_bf16 v[96:111], v[6:9], v[128:131], v[96:111]
	ds_read_b128 v[6:9], v211 offset:24576
	s_waitcnt lgkmcnt(3)
	v_mfma_f32_32x32x16_bf16 v[96:111], v[10:13], v[132:135], v[96:111]
	ds_read_b128 v[10:13], v210 offset:16384
	s_waitcnt lgkmcnt(3)
	v_mfma_f32_32x32x16_bf16 v[96:111], v[250:253], v[136:139], v[96:111]
	ds_read_b128 v[250:253], v211 offset:16384
	s_waitcnt lgkmcnt(3)
	v_mfma_f32_32x32x16_bf16 v[80:95], v[2:5], v[132:135], v[80:95]
	s_waitcnt lgkmcnt(2)
	v_mfma_f32_32x32x16_bf16 v[96:111], v[6:9], v[140:143], v[96:111]
	s_waitcnt lgkmcnt(1)
	v_mfma_f32_32x32x16_bf16 v[80:95], v[10:13], v[136:139], v[80:95]
	s_nop 8
	v_max_f32_e32 v224, v96, v96
	v_max_f32_e32 v223, v97, v97
	v_max_f32_e32 v222, v98, v98
	v_max_f32_e32 v221, v99, v99
	v_max_f32_e32 v220, v100, v100
	v_max_f32_e32 v219, v101, v101
	v_max_f32_e32 v218, v102, v102
	s_waitcnt lgkmcnt(0)
	v_mfma_f32_32x32x16_bf16 v[80:95], v[250:253], v[140:143], v[80:95]
	v_max_f32_e32 v217, v103, v103
	v_max_f32_e32 v216, v104, v104
	v_max_f32_e32 v215, v105, v105
	v_max_f32_e32 v185, v106, v106
	v_max_f32_e32 v183, v107, v107
	v_max_f32_e32 v181, v108, v108
	v_max_f32_e32 v179, v109, v109
	v_max_f32_e32 v177, v110, v110
	v_max_f32_e32 v175, v111, v111
	s_nop 2
	v_max_f32_e32 v111, v80, v80
	v_max_f32_e32 v109, v81, v81
	v_max_f32_e32 v110, v82, v82
	v_max_f32_e32 v108, v83, v83
	v_max_f32_e32 v107, v84, v84
	v_max_f32_e32 v106, v85, v85
	v_max_f32_e32 v105, v86, v86
	v_max_f32_e32 v104, v87, v87
	v_max_f32_e32 v103, v88, v88
	v_max_f32_e32 v102, v89, v89
	v_max_f32_e32 v101, v90, v90
	v_max_f32_e32 v100, v91, v91
	v_max_f32_e32 v99, v92, v92
	v_max_f32_e32 v98, v93, v93
	v_max_f32_e32 v82, v94, v94
	v_max_f32_e32 v1, v95, v95
	s_cbranch_scc1 .LBB0_1343
	v_min_f32_e32 v2, 0x42c80000, v224
	v_exp_f32_e32 v2, v2
	v_min_f32_e32 v3, 0x42c80000, v223
	v_exp_f32_e32 v3, v3
	v_or_b32_e32 v90, s12, v196
	v_add_f32_e32 v4, 1.0, v2
	v_rcp_f32_e32 v4, v4
	v_or_b32_e32 v5, 32, v90
	v_cmp_lt_i32_e32 vcc, v5, v186
	v_min_f32_e32 v5, 0x42c80000, v222
	v_mul_f32_e32 v2, v2, v4
	v_cndmask_b32_e32 v83, 0, v2, vcc
	v_add_f32_e32 v2, 1.0, v3
	v_rcp_f32_e32 v2, v2
	v_exp_f32_e32 v5, v5
	v_cndmask_b32_e32 v11, 1.0, v4, vcc
	v_or_b32_e32 v4, 33, v90
	v_cmp_lt_i32_e32 vcc, v4, v186
	v_min_f32_e32 v4, 0x42c80000, v221
	v_exp_f32_e32 v4, v4
	v_cndmask_b32_e32 v15, 1.0, v2, vcc
	v_mul_f32_e32 v2, v3, v2
	v_cndmask_b32_e32 v88, 0, v2, vcc
	v_add_f32_e32 v2, 1.0, v5
	v_rcp_f32_e32 v2, v2
	v_or_b32_e32 v3, 34, v90
	v_cmp_lt_i32_e32 vcc, v3, v186
	v_or_b32_e32 v3, 35, v90
	v_min_f32_e32 v97, 0x42c80000, v175
	v_cndmask_b32_e32 v81, 1.0, v2, vcc
	v_mul_f32_e32 v2, v5, v2
	v_cndmask_b32_e32 v89, 0, v2, vcc
	v_add_f32_e32 v2, 1.0, v4
	v_rcp_f32_e32 v2, v2
	v_min_f32_e32 v5, 0x42c80000, v220
	v_exp_f32_e32 v5, v5
	v_cmp_lt_i32_e32 vcc, v3, v186
	v_or_b32_e32 v3, 40, v90
	v_exp_f32_e32 v97, v97
	v_cndmask_b32_e32 v85, 1.0, v2, vcc
	v_mul_f32_e32 v2, v4, v2
	v_cndmask_b32_e32 v91, 0, v2, vcc
	v_add_f32_e32 v2, 1.0, v5
	v_rcp_f32_e32 v2, v2
	v_min_f32_e32 v4, 0x42c80000, v219
	v_exp_f32_e32 v4, v4
	v_cmp_lt_i32_e32 vcc, v3, v186
	v_or_b32_e32 v3, 41, v90
	v_add_f32_e32 v227, 1.0, v97
	v_cndmask_b32_e32 v8, 1.0, v2, vcc
	v_mul_f32_e32 v2, v5, v2
	v_cndmask_b32_e32 v92, 0, v2, vcc
	v_add_f32_e32 v2, 1.0, v4
	v_rcp_f32_e32 v2, v2
	v_min_f32_e32 v5, 0x42c80000, v218
	v_exp_f32_e32 v5, v5
	v_cmp_lt_i32_e32 vcc, v3, v186
	v_or_b32_e32 v3, 42, v90
	v_rcp_f32_e32 v227, v227
	v_cndmask_b32_e32 v86, 1.0, v2, vcc
	v_mul_f32_e32 v2, v4, v2
	v_cndmask_b32_e32 v93, 0, v2, vcc
	v_add_f32_e32 v2, 1.0, v5
	v_rcp_f32_e32 v2, v2
	v_min_f32_e32 v4, 0x42c80000, v217
	v_exp_f32_e32 v4, v4
	v_cmp_lt_i32_e32 vcc, v3, v186
	v_or_b32_e32 v3, 43, v90
	v_and_b32_e32 v230, 64, v173
	v_cndmask_b32_e32 v87, 1.0, v2, vcc
	v_mul_f32_e32 v2, v5, v2
	v_cndmask_b32_e32 v94, 0, v2, vcc
	v_add_f32_e32 v2, 1.0, v4
	v_rcp_f32_e32 v2, v2
	v_min_f32_e32 v5, 0x42c80000, v216
	v_exp_f32_e32 v5, v5
	v_cmp_lt_i32_e32 vcc, v3, v186
	v_or_b32_e32 v3, 48, v90
	v_or_b32_e32 v226, 58, v90
	v_cndmask_b32_e32 v95, 1.0, v2, vcc
	v_mul_f32_e32 v2, v4, v2
	v_cndmask_b32_e32 v96, 0, v2, vcc
	v_add_f32_e32 v2, 1.0, v5
	v_rcp_f32_e32 v2, v2
	v_min_f32_e32 v4, 0x42c80000, v215
	v_exp_f32_e32 v4, v4
	v_cmp_lt_i32_e32 vcc, v3, v186
	v_or_b32_e32 v3, 49, v90
	v_or_b32_e32 v228, 59, v90
	v_cndmask_b32_e32 v6, 1.0, v2, vcc
	v_mul_f32_e32 v2, v5, v2
	v_cndmask_b32_e32 v12, 0, v2, vcc
	v_add_f32_e32 v2, 1.0, v4
	v_rcp_f32_e32 v2, v2
	v_min_f32_e32 v5, 0x42c80000, v185
	v_exp_f32_e32 v5, v5
	v_cmp_lt_i32_e32 vcc, v3, v186
	v_or_b32_e32 v3, 50, v90
	v_xor_b32_e32 v229, 32, v173
	v_cndmask_b32_e32 v7, 1.0, v2, vcc
	v_mul_f32_e32 v2, v4, v2
	v_cndmask_b32_e32 v9, 0, v2, vcc
	v_add_f32_e32 v2, 1.0, v5
	v_rcp_f32_e32 v2, v2
	v_min_f32_e32 v4, 0x42c80000, v183
	v_exp_f32_e32 v4, v4
	v_cmp_lt_i32_e32 vcc, v3, v186
	v_or_b32_e32 v3, 51, v90
	v_add_u32_e32 v230, 64, v230
	v_cndmask_b32_e32 v10, 1.0, v2, vcc
	v_mul_f32_e32 v2, v5, v2
	v_cndmask_b32_e32 v13, 0, v2, vcc
	v_add_f32_e32 v2, 1.0, v4
	v_rcp_f32_e32 v2, v2
	v_min_f32_e32 v5, 0x42c80000, v181
	v_exp_f32_e32 v5, v5
	v_cmp_lt_i32_e32 vcc, v3, v186
	v_or_b32_e32 v3, 56, v90
	v_cmp_lt_i32_e64 s[10:11], v228, v186
	v_cndmask_b32_e32 v14, 1.0, v2, vcc
	v_mul_f32_e32 v2, v4, v2
	v_cndmask_b32_e32 v84, 0, v2, vcc
	v_add_f32_e32 v2, 1.0, v5
	v_min_f32_e32 v4, 0x42c80000, v179
	v_rcp_f32_e32 v2, v2
	v_exp_f32_e32 v4, v4
	v_cmp_lt_i32_e32 vcc, v3, v186
	v_cmp_lt_i32_e64 s[12:13], v229, v230
	v_cndmask_b32_e64 v228, 1.0, v227, s[10:11]
	v_cndmask_b32_e32 v3, 1.0, v2, vcc
	v_mul_f32_e32 v2, v5, v2
	v_add_f32_e32 v5, 1.0, v4
	v_rcp_f32_e32 v5, v5
	v_cndmask_b32_e32 v80, 0, v2, vcc
	v_or_b32_e32 v2, 57, v90
	v_cmp_lt_i32_e32 vcc, v2, v186
	v_mul_f32_e32 v4, v4, v5
	v_cndmask_b32_e64 v229, v173, v229, s[12:13]
	v_cndmask_b32_e32 v2, 1.0, v5, vcc
	v_min_f32_e32 v5, 0x42c80000, v177
	v_exp_f32_e32 v5, v5
	v_cndmask_b32_e32 v4, 0, v4, vcc
	v_cmp_lt_i32_e32 vcc, v226, v186
	v_lshlrev_b32_e32 v231, 2, v229
	v_add_f32_e32 v225, 1.0, v5
	v_rcp_f32_e32 v225, v225
	v_mul_f32_e32 v3, v3, v2
	v_mul_f32_e32 v8, v8, v86
	v_cndmask_b32_e32 v226, 1.0, v225, vcc
	v_mul_f32_e32 v229, v226, v228
	v_mul_f32_e32 v229, v3, v229
	v_mov_b32_e32 v254, v229
	s_nop 1
	v_permlane32_swap_b32_e32 v254, v230
	s_nop 1
	v_permlane32_swap_b32_e32 v230, v254
	v_mul_f32_e32 v3, v5, v225
	v_cndmask_b32_e32 v5, 0, v3, vcc
	v_mul_f32_e32 v3, v97, v227
	v_cndmask_b32_e64 v3, 0, v3, s[10:11]
	s_waitcnt lgkmcnt(0)
	v_mul_f32_e32 v97, v171, v230
	v_cndmask_b32_e64 v97, v171, v97, s[6:7]
	v_mul_f32_e32 v225, v228, v97
	v_mul_f32_e32 v226, v226, v225
	v_mul_f32_e32 v227, v2, v226
	v_mul_f32_e32 v2, v5, v225
	v_mul_f32_e32 v5, v6, v7
	v_mul_f32_e32 v6, v10, v14
	v_mul_f32_e32 v3, v3, v97
	v_mul_f32_e32 v97, v5, v6
	v_mov_b32_e32 v254, v97
	s_nop 1
	v_permlane32_swap_b32_e32 v254, v225
	s_nop 1
	v_permlane32_swap_b32_e32 v225, v254
	v_mul_f32_e32 v6, v229, v230
	v_mul_f32_e32 v5, v4, v226
	v_mul_f32_e32 v4, v80, v227
	v_mul_f32_e32 v80, v171, v6
	s_waitcnt lgkmcnt(0)
	v_mul_f32_e32 v6, v80, v225
	v_cndmask_b32_e64 v6, v80, v6, s[6:7]
	v_mul_f32_e32 v14, v14, v6
	v_mul_f32_e32 v226, v10, v14
	v_mul_f32_e32 v10, v87, v95
	v_mul_f32_e32 v10, v8, v10
	v_mul_f32_e32 v227, v7, v226
	v_mul_f32_e32 v7, v84, v6
	v_mul_f32_e32 v6, v13, v14
	v_mov_b32_e32 v254, v10
	s_nop 1
	v_permlane32_swap_b32_e32 v254, v14
	s_nop 1
	v_permlane32_swap_b32_e32 v14, v254
	v_mul_f32_e32 v84, v97, v225
	v_mul_f32_e32 v8, v12, v227
	v_pk_mul_f32 v[12:13], v[80:81], v[84:85]
	v_cmp_lt_i32_e32 vcc, v90, v186
	s_waitcnt lgkmcnt(0)
	v_mul_f32_e32 v80, v12, v14
	v_cndmask_b32_e64 v80, v12, v80, s[6:7]
	v_mul_f32_e32 v84, v95, v80
	v_mul_f32_e32 v95, v87, v84
	v_pk_mul_f32 v[10:11], v[10:11], v[14:15]
	v_mul_f32_e32 v97, v86, v95
	v_pk_mul_f32 v[86:87], v[10:11], v[12:13]
	v_mov_b32_e32 v254, v87
	s_nop 1
	v_permlane32_swap_b32_e32 v254, v225
	s_nop 1
	v_permlane32_swap_b32_e32 v225, v254
	v_mul_f32_e32 v11, v96, v80
	v_mul_f32_e32 v10, v94, v84
	v_mul_f32_e32 v9, v9, v226
	v_mul_f32_e32 v12, v92, v97
	s_waitcnt lgkmcnt(0)
	v_mul_f32_e32 v14, v86, v225
	v_cndmask_b32_e64 v14, v86, v14, s[6:7]
	v_mul_f32_e32 v80, v85, v14
	v_mul_f32_e32 v81, v81, v80
	v_mul_f32_e32 v84, v15, v81
	v_mul_f32_e32 v15, v91, v14
	v_mul_f32_e32 v14, v89, v80
	v_min_f32_e32 v80, 0x42c80000, v111
	v_exp_f32_e32 v85, v80
	v_mul_f32_e32 v80, v83, v84
	v_min_f32_e32 v84, 0x42c80000, v109
	v_exp_f32_e32 v84, v84
	v_add_f32_e32 v83, 1.0, v85
	v_rcp_f32_e32 v83, v83
	v_mul_f32_e32 v81, v88, v81
	v_mul_f32_e32 v88, v87, v225
	v_min_f32_e32 v87, 0x42c80000, v110
	v_cndmask_b32_e32 v245, 1.0, v83, vcc
	v_mul_f32_e32 v83, v85, v83
	v_cndmask_b32_e32 v225, 0, v83, vcc
	v_add_f32_e32 v83, 1.0, v84
	v_rcp_f32_e32 v85, v83
	v_exp_f32_e32 v87, v87
	v_or_b32_e32 v83, 1, v90
	v_cmp_lt_i32_e32 vcc, v83, v186
	v_mul_f32_e32 v84, v84, v85
	v_min_f32_e32 v89, 0x42c80000, v108
	v_cndmask_b32_e32 v230, 0, v84, vcc
	v_add_f32_e32 v84, 1.0, v87
	v_rcp_f32_e32 v84, v84
	v_cndmask_b32_e32 v83, 1.0, v85, vcc
	v_or_b32_e32 v85, 2, v90
	v_exp_f32_e32 v89, v89
	v_cmp_lt_i32_e32 vcc, v85, v186
	v_or_b32_e32 v85, 3, v90
	v_mul_f32_e32 v13, v93, v95
	v_cndmask_b32_e32 v226, 1.0, v84, vcc
	v_mul_f32_e32 v84, v87, v84
	v_min_f32_e32 v87, 0x42c80000, v107
	v_exp_f32_e32 v87, v87
	v_cndmask_b32_e32 v227, 0, v84, vcc
	v_add_f32_e32 v84, 1.0, v89
	v_rcp_f32_e32 v84, v84
	v_cmp_lt_i32_e32 vcc, v85, v186
	v_add_f32_e32 v85, 1.0, v87
	v_rcp_f32_e32 v85, v85
	v_cndmask_b32_e32 v228, 1.0, v84, vcc
	v_mul_f32_e32 v84, v89, v84
	v_cndmask_b32_e32 v229, 0, v84, vcc
	v_or_b32_e32 v84, 8, v90
	v_cmp_lt_i32_e32 vcc, v84, v186
	v_mul_f32_e32 v84, v87, v85
	v_or_b32_e32 v89, 11, v90
	v_cndmask_b32_e32 v97, 1.0, v85, vcc
	v_min_f32_e32 v85, 0x42c80000, v106
	v_exp_f32_e32 v92, v85
	v_min_f32_e32 v85, 0x42c80000, v105
	v_cndmask_b32_e32 v96, 0, v84, vcc
	v_exp_f32_e32 v93, v85
	v_add_f32_e32 v84, 1.0, v92
	v_rcp_f32_e32 v94, v84
	v_min_f32_e32 v84, 0x42c80000, v104
	v_exp_f32_e32 v84, v84
	v_min_f32_e32 v85, 0x42c80000, v103
	v_exp_f32_e32 v85, v85
	v_add_f32_e32 v87, 1.0, v93
	v_rcp_f32_e32 v95, v87
	v_add_f32_e32 v87, 1.0, v84
	v_rcp_f32_e32 v232, v87
	v_add_f32_e32 v87, 1.0, v85
	v_rcp_f32_e32 v233, v87
	v_or_b32_e32 v87, 16, v90
	v_cmp_lt_i32_e64 s[10:11], v87, v169
	v_min_f32_e32 v87, 0x42c80000, v100
	v_exp_f32_e32 v238, v87
	v_min_f32_e32 v87, 0x42c80000, v99
	v_exp_f32_e32 v239, v87
	v_cmp_lt_i32_e32 vcc, v89, v186
	v_add_f32_e32 v87, 1.0, v238
	v_rcp_f32_e32 v240, v87
	v_add_f32_e32 v87, 1.0, v239
	v_rcp_f32_e32 v241, v87
	v_pk_mul_f32 v[84:85], v[84:85], v[232:233]
	v_or_b32_e32 v89, 19, v90
	v_cndmask_b32_e32 v247, 1.0, v232, vcc
	v_cndmask_b32_e32 v232, 0, v84, vcc
	v_or_b32_e32 v87, 24, v90
	v_cmp_lt_i32_e32 vcc, v89, v186
	v_min_f32_e32 v91, 0x42c80000, v98
	v_cndmask_b32_e64 v235, 1.0, v233, s[10:11]
	v_cndmask_b32_e64 v233, 0, v85, s[10:11]
	v_cndmask_b32_e32 v89, 1.0, v240, vcc
	v_cmp_lt_i32_e64 s[10:11], v87, v169
	v_pk_mul_f32 v[238:239], v[238:239], v[240:241]
	v_exp_f32_e32 v240, v91
	v_min_f32_e32 v91, 0x42c80000, v82
	v_cndmask_b32_e64 v87, 1.0, v241, s[10:11]
	v_exp_f32_e32 v241, v91
	v_min_f32_e32 v91, 0x42c80000, v1
	v_exp_f32_e32 v91, v91
	v_add_f32_e32 v234, 1.0, v240
	v_rcp_f32_e32 v242, v234
	v_add_f32_e32 v234, 1.0, v241
	v_add_f32_e32 v243, 1.0, v91
	v_rcp_f32_e32 v244, v243
	v_min_f32_e32 v85, 0x42c80000, v102
	v_rcp_f32_e32 v243, v234
	v_or_b32_e32 v234, 27, v90
	v_exp_f32_e32 v236, v85
	v_min_f32_e32 v85, 0x42c80000, v101
	v_cndmask_b32_e32 v238, 0, v238, vcc
	v_cmp_lt_i32_e32 vcc, v234, v186
	v_mul_f32_e32 v91, v91, v244
	v_exp_f32_e32 v237, v85
	v_cndmask_b32_e32 v248, 1.0, v244, vcc
	v_cndmask_b32_e32 v244, 0, v91, vcc
	v_or_b32_e32 v91, 26, v90
	v_or_b32_e32 v234, 25, v90
	v_cndmask_b32_e64 v239, 0, v239, s[10:11]
	v_cmp_lt_i32_e32 vcc, v234, v186
	v_cmp_lt_i32_e64 s[10:11], v91, v169
	v_add_f32_e32 v84, 1.0, v236
	v_cndmask_b32_e32 v249, 1.0, v242, vcc
	v_cndmask_b32_e64 v91, 1.0, v243, s[10:11]
	v_mul_f32_e32 v87, v87, v249
	v_mul_f32_e32 v234, v91, v248
	v_add_f32_e32 v85, 1.0, v237
	v_mul_f32_e32 v234, v87, v234
	v_rcp_f32_e32 v84, v84
	v_rcp_f32_e32 v85, v85
	v_pk_mul_f32 v[240:241], v[240:241], v[242:243]
	v_mov_b32_e32 v254, v234
	s_nop 1
	v_permlane32_swap_b32_e32 v254, v242
	s_nop 1
	v_permlane32_swap_b32_e32 v242, v254
	v_or_b32_e32 v87, 18, v90
	v_or_b32_e32 v243, 17, v90
	v_cndmask_b32_e64 v241, 0, v241, s[10:11]
	v_cndmask_b32_e32 v240, 0, v240, vcc
	v_cmp_lt_i32_e32 vcc, v243, v186
	v_cmp_lt_i32_e64 s[10:11], v87, v169
	v_pk_mul_f32 v[92:93], v[92:93], v[94:95]
	v_cndmask_b32_e32 v243, 1.0, v84, vcc
	v_cndmask_b32_e64 v87, 1.0, v85, s[10:11]
	v_pk_mul_f32 v[84:85], v[236:237], v[84:85]
	s_waitcnt lgkmcnt(0)
	v_pk_mul_f32 v[234:235], v[234:235], v[242:243]
	v_cndmask_b32_e64 v237, 0, v85, s[10:11]
	v_cndmask_b32_e32 v236, 0, v84, vcc
	v_pk_mul_f32 v[84:85], v[86:87], v[88:89]
	v_mul_f32_e32 v245, v245, v83
	v_pk_mul_f32 v[234:235], v[234:235], v[84:85]
	v_mul_f32_e32 v86, v84, v242
	v_mov_b32_e32 v254, v235
	s_nop 1
	v_permlane32_swap_b32_e32 v254, v242
	s_nop 1
	v_permlane32_swap_b32_e32 v242, v254
	v_cndmask_b32_e64 v246, v84, v86, s[6:7]
	v_mul_f32_e32 v85, v248, v246
	v_mul_f32_e32 v84, v91, v85
	v_mul_f32_e32 v249, v249, v84
	s_waitcnt lgkmcnt(0)
	v_mul_f32_e32 v86, v234, v242
	v_cndmask_b32_e64 v248, v234, v86, s[6:7]
	v_mul_f32_e32 v89, v89, v248
	v_mul_f32_e32 v88, v87, v89
	v_mul_f32_e32 v91, v243, v88
	v_pk_mul_f32 v[88:89], v[236:237], v[88:89]
	v_or_b32_e32 v237, 10, v90
	v_or_b32_e32 v90, 9, v90
	v_cmp_lt_i32_e32 vcc, v90, v186
	v_cmp_lt_i32_e64 s[10:11], v237, v169
	v_pk_mul_f32 v[86:87], v[238:239], v[248:249]
	v_cndmask_b32_e32 v236, 1.0, v94, vcc
	v_cndmask_b32_e64 v238, 1.0, v95, s[10:11]
	v_mul_f32_e32 v90, v97, v236
	v_mul_f32_e32 v97, v238, v247
	v_mul_f32_e32 v239, v90, v97
	v_mov_b32_e32 v254, v239
	s_nop 1
	v_permlane32_swap_b32_e32 v254, v237
	s_nop 1
	v_permlane32_swap_b32_e32 v237, v254
	v_mul_f32_e32 v235, v235, v242
	v_mul_f32_e32 v97, v234, v235
	v_cndmask_b32_e64 v93, 0, v93, s[10:11]
	v_cndmask_b32_e32 v92, 0, v92, vcc
	s_waitcnt lgkmcnt(0)
	v_mul_f32_e32 v90, v97, v237
	v_cndmask_b32_e64 v90, v97, v90, s[6:7]
	v_mul_f32_e32 v235, v247, v90
	v_mul_f32_e32 v234, v238, v235
	v_mul_f32_e32 v247, v226, v228
	v_pk_mul_f32 v[94:95], v[92:93], v[234:235]
	v_pk_mul_f32 v[92:93], v[244:245], v[246:247]
	v_mov_b32_e32 v254, v93
	s_nop 1
	v_permlane32_swap_b32_e32 v254, v231
	s_nop 1
	v_permlane32_swap_b32_e32 v231, v254
	v_mov_b32_e32 v235, v239
	v_pk_mul_f32 v[90:91], v[232:233], v[90:91]
	v_pk_mul_f32 v[232:233], v[234:235], v[236:237]
	v_pk_mul_f32 v[84:85], v[240:241], v[84:85]
	v_pk_mul_f32 v[96:97], v[96:97], v[232:233]
	s_mov_b64 s[10:11], 0
.LBB0_1343:
	s_andn2_b64 vcc, exec, s[10:11]
	s_cbranch_vccnz .LBB0_1345
	v_min_f32_e32 v83, 0x42c80000, v216
	v_exp_f32_e32 v84, v83
	v_min_f32_e32 v83, 0x42c80000, v215
	v_exp_f32_e32 v85, v83
	v_min_f32_e32 v89, 0x42c80000, v181
	v_add_f32_e32 v83, 1.0, v84
	v_exp_f32_e32 v90, v89
	v_min_f32_e32 v89, 0x42c80000, v179
	v_rcp_f32_e32 v86, v83
	v_add_f32_e32 v83, 1.0, v85
	v_exp_f32_e32 v91, v89
	v_min_f32_e32 v93, 0x42c80000, v177
	v_rcp_f32_e32 v87, v83
	v_min_f32_e32 v83, 0x42c80000, v185
	v_exp_f32_e32 v94, v93
	v_min_f32_e32 v93, 0x42c80000, v175
	v_exp_f32_e32 v88, v83
	v_min_f32_e32 v83, 0x42c80000, v183
	v_exp_f32_e32 v95, v93
	v_exp_f32_e32 v89, v83
	v_add_f32_e32 v83, 1.0, v90
	v_rcp_f32_e32 v92, v83
	v_add_f32_e32 v83, 1.0, v91
	v_rcp_f32_e32 v96, v83
	v_add_f32_e32 v83, 1.0, v94
	v_rcp_f32_e32 v93, v83
	v_add_f32_e32 v83, 1.0, v95
	v_rcp_f32_e32 v97, v83
	v_and_b32_e32 v175, 64, v173
	v_min_f32_e32 v10, 0x42c80000, v220
	v_min_f32_e32 v11, 0x42c80000, v219
	v_min_f32_e32 v14, 0x42c80000, v218
	v_min_f32_e32 v15, 0x42c80000, v217
	v_xor_b32_e32 v83, 32, v173
	v_add_u32_e32 v175, 64, v175
	v_exp_f32_e32 v10, v10
	v_exp_f32_e32 v11, v11
	v_exp_f32_e32 v14, v14
	v_exp_f32_e32 v15, v15
	v_cmp_lt_i32_e32 vcc, v83, v175
	v_pk_mul_f32 v[216:217], v[92:93], v[96:97]
	v_add_f32_e32 v177, 1.0, v88
	v_cndmask_b32_e32 v83, v173, v83, vcc
	v_lshlrev_b32_e32 v173, 2, v83
	v_mul_f32_e32 v83, v216, v217
	v_mov_b32_e32 v254, v83
	s_nop 1
	v_permlane32_swap_b32_e32 v254, v175
	s_nop 1
	v_permlane32_swap_b32_e32 v175, v254
	v_rcp_f32_e32 v216, v177
	v_add_f32_e32 v177, 1.0, v89
	v_add_f32_e32 v12, 1.0, v10
	v_add_f32_e32 v13, 1.0, v11
	v_add_f32_e32 v80, 1.0, v14
	v_add_f32_e32 v81, 1.0, v15
	v_rcp_f32_e32 v217, v177
	v_rcp_f32_e32 v12, v12
	v_rcp_f32_e32 v13, v13
	v_rcp_f32_e32 v80, v80
	v_rcp_f32_e32 v81, v81
	v_min_f32_e32 v2, 0x42c80000, v224
	v_min_f32_e32 v3, 0x42c80000, v223
	v_min_f32_e32 v6, 0x42c80000, v222
	v_min_f32_e32 v7, 0x42c80000, v221
	v_exp_f32_e32 v2, v2
	v_exp_f32_e32 v3, v3
	v_exp_f32_e32 v6, v6
	v_exp_f32_e32 v7, v7
	s_waitcnt lgkmcnt(0)
	v_mul_f32_e32 v177, v171, v175
	v_mov_b32_e32 v224, v87
	v_mov_b32_e32 v225, v217
	v_mov_b32_e32 v226, v86
	v_mov_b32_e32 v227, v216
	v_cndmask_b32_e64 v219, v171, v177, s[6:7]
	v_pk_mul_f32 v[224:225], v[226:227], v[224:225]
	v_mov_b32_e32 v228, v13
	v_mov_b32_e32 v229, v81
	v_mov_b32_e32 v230, v12
	v_mov_b32_e32 v231, v80
	v_mov_b32_e32 v221, v97
	v_mul_f32_e32 v218, v97, v219
	v_mul_f32_e32 v97, v224, v225
	v_pk_mul_f32 v[228:229], v[230:231], v[228:229]
	v_add_f32_e32 v4, 1.0, v2
	v_add_f32_e32 v5, 1.0, v3
	v_add_f32_e32 v8, 1.0, v6
	v_add_f32_e32 v9, 1.0, v7
	v_mov_b32_e32 v254, v97
	s_nop 1
	v_permlane32_swap_b32_e32 v254, v177
	s_nop 1
	v_permlane32_swap_b32_e32 v177, v254
	v_pk_mul_f32 v[228:229], v[228:229], v[228:229] op_sel:[0,1] op_sel_hi:[1,0]
	v_rcp_f32_e32 v4, v4
	v_rcp_f32_e32 v5, v5
	v_rcp_f32_e32 v8, v8
	v_rcp_f32_e32 v9, v9
	v_mov_b32_e32 v254, v228
	s_nop 1
	v_permlane32_swap_b32_e32 v254, v230
	s_nop 1
	v_permlane32_swap_b32_e32 v230, v254
	v_mov_b32_e32 v220, v93
	v_mul_f32_e32 v93, v93, v218
	v_mul_f32_e32 v83, v83, v175
	v_mov_b32_e32 v222, v92
	v_mov_b32_e32 v223, v96
	v_mul_f32_e32 v92, v96, v93
	v_mul_f32_e32 v96, v171, v83
	s_waitcnt lgkmcnt(1)
	v_mul_f32_e32 v83, v96, v177
	v_mul_f32_e32 v232, v97, v177
	v_mov_b32_e32 v97, v8
	v_mov_b32_e32 v233, v9
	v_mov_b32_e32 v229, v4
	v_mov_b32_e32 v231, v5
	v_cndmask_b32_e64 v225, v96, v83, s[6:7]
	v_pk_mul_f32 v[96:97], v[96:97], v[232:233]
	s_waitcnt lgkmcnt(0)
	v_pk_mul_f32 v[228:229], v[228:229], v[230:231]
	v_mul_f32_e32 v83, v96, v230
	v_pk_mul_f32 v[230:231], v[228:229], v[96:97]
	v_mov_b32_e32 v254, v231
	s_nop 1
	v_permlane32_swap_b32_e32 v254, v171
	s_nop 1
	v_permlane32_swap_b32_e32 v171, v254
	v_cndmask_b32_e64 v97, v96, v83, s[6:7]
	v_mul_f32_e32 v96, v81, v97
	v_pk_mul_f32 v[2:3], v[2:3], v[4:5]
	v_mul_f32_e32 v229, v80, v96
	s_waitcnt lgkmcnt(0)
	v_mul_f32_e32 v83, v230, v171
	v_cndmask_b32_e64 v233, v230, v83, s[6:7]
	v_mul_f32_e32 v232, v9, v233
	v_mul_f32_e32 v235, v8, v232
	v_mul_f32_e32 v234, v5, v235
	v_pk_mul_f32 v[4:5], v[6:7], v[8:9]
	v_pk_mul_f32 v[8:9], v[14:15], v[80:81]
	v_pk_mul_f32 v[80:81], v[2:3], v[234:235]
	v_min_f32_e32 v2, 0x42c80000, v111
	v_exp_f32_e32 v83, v2
	v_mul_f32_e32 v224, v217, v225
	v_mul_f32_e32 v227, v216, v224
	v_mul_f32_e32 v226, v87, v227
	v_pk_mul_f32 v[84:85], v[84:85], v[86:87]
	v_pk_mul_f32 v[6:7], v[10:11], v[12:13]
	v_pk_mul_f32 v[86:87], v[88:89], v[216:217]
	v_pk_mul_f32 v[88:89], v[90:91], v[222:223]
	v_pk_mul_f32 v[90:91], v[94:95], v[220:221]
	v_pk_mul_f32 v[10:11], v[8:9], v[96:97]
	v_pk_mul_f32 v[8:9], v[84:85], v[226:227]
	v_add_f32_e32 v84, 1.0, v83
	v_pk_mul_f32 v[2:3], v[90:91], v[218:219]
	v_rcp_f32_e32 v91, v84
	v_min_f32_e32 v85, 0x42c80000, v110
	v_exp_f32_e32 v85, v85
	v_mul_f32_e32 v228, v13, v229
	v_pk_mul_f32 v[12:13], v[6:7], v[228:229]
	v_pk_mul_f32 v[6:7], v[86:87], v[224:225]
	v_mul_f32_e32 v225, v83, v91
	v_min_f32_e32 v83, 0x42c80000, v109
	v_mul_f32_e32 v84, v231, v171
	v_exp_f32_e32 v171, v83
	v_add_f32_e32 v83, 1.0, v85
	v_rcp_f32_e32 v226, v83
	v_min_f32_e32 v83, 0x42c80000, v108
	v_exp_f32_e32 v87, v83
	v_pk_mul_f32 v[14:15], v[4:5], v[232:233]
	v_mul_f32_e32 v227, v85, v226
	v_pk_mul_f32 v[4:5], v[88:89], v[92:93]
	v_add_f32_e32 v85, 1.0, v87
	v_rcp_f32_e32 v228, v85
	v_min_f32_e32 v85, 0x42c80000, v107
	v_exp_f32_e32 v86, v85
	v_min_f32_e32 v85, 0x42c80000, v106
	v_exp_f32_e32 v88, v85
	v_mul_f32_e32 v229, v87, v228
	v_min_f32_e32 v87, 0x42c80000, v104
	v_exp_f32_e32 v96, v87
	v_min_f32_e32 v87, 0x42c80000, v103
	v_add_f32_e32 v85, 1.0, v86
	v_exp_f32_e32 v97, v87
	v_rcp_f32_e32 v92, v85
	v_add_f32_e32 v85, 1.0, v88
	v_rcp_f32_e32 v94, v85
	v_min_f32_e32 v85, 0x42c80000, v105
	v_exp_f32_e32 v89, v85
	v_add_f32_e32 v85, 1.0, v96
	v_rcp_f32_e32 v104, v85
	v_add_f32_e32 v85, 1.0, v97
	v_rcp_f32_e32 v105, v85
	v_min_f32_e32 v85, 0x42c80000, v102
	v_exp_f32_e32 v102, v85
	v_min_f32_e32 v87, 0x42c80000, v101
	v_exp_f32_e32 v103, v87
	v_min_f32_e32 v87, 0x42c80000, v100
	v_exp_f32_e32 v100, v87
	v_min_f32_e32 v87, 0x42c80000, v99
	v_min_f32_e32 v82, 0x42c80000, v82
	v_add_f32_e32 v85, 1.0, v89
	v_exp_f32_e32 v101, v87
	v_min_f32_e32 v87, 0x42c80000, v98
	v_exp_f32_e32 v99, v82
	v_min_f32_e32 v1, 0x42c80000, v1
	v_rcp_f32_e32 v95, v85
	v_add_f32_e32 v85, 1.0, v102
	v_exp_f32_e32 v98, v87
	v_exp_f32_e32 v90, v1
	v_rcp_f32_e32 v106, v85
	v_add_f32_e32 v85, 1.0, v103
	v_rcp_f32_e32 v107, v85
	v_add_f32_e32 v85, 1.0, v100
	v_rcp_f32_e32 v108, v85
	v_add_f32_e32 v85, 1.0, v101
	v_add_f32_e32 v1, 1.0, v99
	v_rcp_f32_e32 v109, v85
	v_add_f32_e32 v85, 1.0, v98
	v_rcp_f32_e32 v111, v1
	v_add_f32_e32 v1, 1.0, v90
	v_rcp_f32_e32 v110, v85
	v_rcp_f32_e32 v82, v1
	v_mov_b32_e32 v218, v109
	v_mov_b32_e32 v219, v111
	v_mov_b32_e32 v220, v110
	v_mov_b32_e32 v221, v82
	v_pk_mul_f32 v[218:219], v[218:219], v[220:221]
	v_pk_mul_f32 v[216:217], v[88:89], v[94:95]
	v_pk_mul_f32 v[218:219], v[218:219], v[218:219] op_sel:[0,1] op_sel_hi:[1,0]
	v_mov_b32_e32 v254, v218
	s_nop 1
	v_permlane32_swap_b32_e32 v254, v220
	s_nop 1
	v_permlane32_swap_b32_e32 v220, v254
	v_mov_b32_e32 v93, v95
	v_mov_b32_e32 v88, v94
	v_mov_b32_e32 v89, v104
	v_mov_b32_e32 v231, v107
	v_mov_b32_e32 v85, v108
	v_mov_b32_e32 v219, v105
	v_mov_b32_e32 v221, v106
	v_pk_mul_f32 v[88:89], v[92:93], v[88:89]
	v_pk_mul_f32 v[84:85], v[230:231], v[84:85]
	s_waitcnt lgkmcnt(0)
	v_pk_mul_f32 v[218:219], v[218:219], v[220:221]
	v_pk_mul_f32 v[88:89], v[88:89], v[88:89] op_sel:[0,1] op_sel_hi:[1,0]
	v_pk_mul_f32 v[218:219], v[218:219], v[84:85]
	v_mov_b32_e32 v254, v88
	s_nop 1
	v_permlane32_swap_b32_e32 v254, v93
	s_nop 1
	v_permlane32_swap_b32_e32 v93, v254
	v_mov_b32_e32 v254, v219
	s_nop 1
	v_permlane32_swap_b32_e32 v254, v1
	s_nop 1
	v_permlane32_swap_b32_e32 v1, v254
	v_add_f32_e32 v83, 1.0, v171
	v_mul_f32_e32 v85, v84, v220
	v_rcp_f32_e32 v83, v83
	v_cndmask_b32_e64 v220, v84, v85, s[6:7]
	v_mov_b32_e32 v87, v88
	v_mul_f32_e32 v85, v82, v220
	s_waitcnt lgkmcnt(1)
	v_pk_mul_f32 v[222:223], v[86:87], v[92:93]
	s_waitcnt lgkmcnt(0)
	v_mul_f32_e32 v92, v219, v1
	v_mul_f32_e32 v84, v111, v85
	v_mul_f32_e32 v1, v218, v1
	v_pk_mul_f32 v[100:101], v[100:101], v[108:109]
	v_mul_f32_e32 v87, v110, v84
	v_cndmask_b32_e64 v86, v218, v1, s[6:7]
	v_mul_f32_e32 v221, v226, v228
	v_mul_f32_e32 v89, v108, v86
	v_pk_mul_f32 v[86:87], v[100:101], v[86:87]
	v_mul_f32_e32 v101, v218, v92
	v_pk_mul_f32 v[90:91], v[90:91], v[82:83]
	v_pk_mul_f32 v[98:99], v[98:99], v[110:111]
	v_mul_f32_e32 v1, v101, v93
	v_pk_mul_f32 v[92:93], v[90:91], v[220:221]
	v_pk_mul_f32 v[102:103], v[102:103], v[106:107]
	v_pk_mul_f32 v[84:85], v[98:99], v[84:85]
	v_mul_f32_e32 v88, v107, v89
	v_cndmask_b32_e64 v98, v101, v1, s[6:7]
	v_mov_b32_e32 v254, v93
	s_nop 1
	v_permlane32_swap_b32_e32 v254, v231
	s_nop 1
	v_permlane32_swap_b32_e32 v231, v254
	v_mul_f32_e32 v99, v106, v88
	v_pk_mul_f32 v[88:89], v[102:103], v[88:89]
	v_mul_f32_e32 v103, v104, v98
	v_mul_f32_e32 v102, v95, v103
	v_pk_mul_f32 v[96:97], v[96:97], v[104:105]
	v_mul_f32_e32 v100, v94, v102
	v_mul_f32_e32 v230, v171, v83
	v_pk_mul_f32 v[90:91], v[96:97], v[98:99]
	v_pk_mul_f32 v[94:95], v[216:217], v[102:103]
	v_pk_mul_f32 v[96:97], v[222:223], v[100:101]
